# C5 + attention: key batches 1,2 loaded into own registers together with batch 0, batch 3 right after batch 0 is consumed (was 4 serial round trips)
# baseline (speedup 1.0000x reference)
; __device__ __forceinline__ f32x4 mfma16(bf16x8 a, bf16x8 b, f32x4 c) { return __builtin_amdgcn_mfma_f32_16x16x32_bf16(a, b, c, 0, 0, 0); }
; __device__ __forceinline__ void phase_attn(const Args& a, unsigned char* smem, int tid, int lane, int wave, bf16_t* Yout) {
;     ...
;             const int r = rbase + (u >> 2), qt = u & 3;
;             const int c0 = qt * 16, kc0 = min(max(c0 - 8, 0), 32), rs = min(max(r - 4, 0), 248);
;             const int qc = c0 + q16, cs = min(max(qc - 8, 0), 48);
;             const size_t qrow = (size_t)b * 16384 + r * 64 + qc;
;             const bf16x8 qf0 = *(const bf16x8*)(AQ + qrow * 1024 + h * 64 + 8 * g), qf1 = *(const bf16x8*)(AQ + qrow * 1024 + h * 64 + 32 + 8 * g);
;             f32x4 st[32];
;             bf16x8 kbuf[1][8];
;     ...
; #pragma unroll
;             for (int bt = 0; bt < 4; ++bt) {
;                 ATT_KLOAD(bt, 0);
;                 asm volatile("" ::: "memory");
; #pragma unroll
;                 for (int ii = 0; ii < 2; ++ii) {
;                     const int i = bt * 2 + ii;
;                     const float* rp = rpb_s + (rs + i - r + 7) * 31;
; #pragma unroll
;                     for (int hf = 0; hf < 2; ++hf) {
;                         f32x4 s = {0.f, 0.f, 0.f, 0.f};
;                         s = mfma16(kbuf[0][(ii * 2 + hf) * 2], qf0, s); s = mfma16(kbuf[0][(ii * 2 + hf) * 2 + 1], qf1, s);
; #pragma unroll
;                         for (int e = 0; e < 4; ++e) { const int kc = kc0 + 8 * g + 4 * hf + e; const bool ok = (kc >= cs) && (kc < cs + 16);
;                             const int dc = min(max(kc - qc + 15, 0), 30);
;                             s[e] = ok ? s[e] * 0.125f + rp[dc] : -1e30f; }
;                         st[i * 2 + hf] = s;
.LBB0_335:
	s_max_i32 s1, s53, 4
	s_and_b32 s3, s55, 48
	s_add_i32 s1, s1, -4
	v_sub_u32_e64 v0, s3, 8 clamp
	s_min_u32 s1, s1, 0xf8
	v_min_u32_e32 v114, 32, v0
	v_lshl_add_u64 v[36:37], v[128:129], 0, v[114:115]
	s_lshl_b32 s12, s1, 6
	v_lshl_add_u64 v[0:1], v[136:137], 0, v[134:135]
	v_lshl_add_u64 v[8:9], v[36:37], 0, s[12:13]
	v_add_co_u32_e32 v0, vcc, s46, v0
	v_lshlrev_b64 v[8:9], 11, v[8:9]
	s_nop 0
	v_addc_co_u32_e32 v1, vcc, 0, v1, vcc
	v_lshl_add_u64 v[8:9], v[130:131], 0, v[8:9]
	global_load_dwordx4 v[4:7], v[0:1], off
	s_nop 0
	global_load_dwordx4 v[0:3], v[0:1], off offset:64
	s_nop 0
	global_load_dwordx4 v[32:35], v[8:9], off
	global_load_dwordx4 v[38:41], v[8:9], off offset:64
	v_add_co_u32_e32 v8, vcc, s19, v8
	s_add_i32 s6, s12, 64
	s_nop 0
	v_addc_co_u32_e32 v9, vcc, 0, v9, vcc
	s_mov_b32 s7, s13
	global_load_dwordx4 v[28:31], v[8:9], off
	global_load_dwordx4 v[24:27], v[8:9], off offset:64
	v_lshl_add_u64 v[8:9], v[36:37], 0, s[6:7]
	v_lshlrev_b64 v[8:9], 11, v[8:9]
	v_lshl_add_u64 v[8:9], v[130:131], 0, v[8:9]
	global_load_dwordx4 v[20:23], v[8:9], off
	global_load_dwordx4 v[16:19], v[8:9], off offset:64
	v_add_co_u32_e32 v8, vcc, s19, v8
	v_or_b32_e32 v45, s3, v123
	s_nop 0
	v_addc_co_u32_e32 v9, vcc, 0, v9, vcc
	global_load_dwordx4 v[12:15], v[8:9], off
	s_nop 0
	global_load_dwordx4 v[8:11], v[8:9], off offset:64
	s_add_i32 s38, s12, 0x80
	s_mov_b32 s39, s13
	v_lshl_add_u64 v[208:209], v[36:37], 0, s[38:39]
	s_add_i32 s38, s12, 0xc0
	v_lshlrev_b64 v[208:209], 11, v[208:209]
	v_lshl_add_u64 v[214:215], v[36:37], 0, s[38:39]
	v_lshl_add_u64 v[208:209], v[130:131], 0, v[208:209]
	v_lshlrev_b64 v[214:215], 11, v[214:215]
	s_mov_b32 s38, 0x2000
	s_mov_b32 s39, 0
	v_lshl_add_u64 v[214:215], v[130:131], 0, v[214:215]
	v_lshl_add_u64 v[210:211], v[208:209], 0, s[38:39]
	v_lshl_add_u64 v[212:213], v[214:215], 0, s[38:39]
	global_load_dwordx4 v[184:187], v[208:209], off
	global_load_dwordx4 v[188:191], v[208:209], off offset:64
	global_load_dwordx4 v[192:195], v[210:211], off
	global_load_dwordx4 v[196:199], v[210:211], off offset:64
	global_load_dwordx4 v[200:203], v[214:215], off
	global_load_dwordx4 v[204:207], v[214:215], off offset:64
	global_load_dwordx4 v[208:211], v[212:213], off
	global_load_dwordx4 v[212:215], v[212:213], off offset:64
	s_add_i32 s38, s12, 0x100
	s_mov_b32 s39, s13
	v_lshl_add_u64 v[236:237], v[36:37], 0, s[38:39]
	s_add_i32 s38, s12, 0x140
	v_lshlrev_b64 v[236:237], 11, v[236:237]
	v_lshl_add_u64 v[242:243], v[36:37], 0, s[38:39]
	v_lshl_add_u64 v[236:237], v[130:131], 0, v[236:237]
	v_lshlrev_b64 v[242:243], 11, v[242:243]
	s_mov_b32 s38, 0x2000
	s_mov_b32 s39, 0
	v_lshl_add_u64 v[242:243], v[130:131], 0, v[242:243]
	v_lshl_add_u64 v[238:239], v[236:237], 0, s[38:39]
	v_lshl_add_u64 v[240:241], v[242:243], 0, s[38:39]
	global_load_dwordx4 v[52:55], v[236:237], off
	global_load_dwordx4 v[56:59], v[236:237], off offset:64
	global_load_dwordx4 v[60:63], v[238:239], off
	global_load_dwordx4 v[64:67], v[238:239], off offset:64
	global_load_dwordx4 v[228:231], v[242:243], off
	global_load_dwordx4 v[232:235], v[242:243], off offset:64
	global_load_dwordx4 v[236:239], v[240:241], off
	global_load_dwordx4 v[240:243], v[240:241], off offset:64
	v_max_i32_e32 v42, 8, v45
	v_add_u32_e32 v42, -8, v42
	s_add_i32 s1, s1, s54
	v_min_u32_e32 v46, 48, v42
	v_add_u32_e32 v47, v114, v157
	s_mulk_i32 s1, 0x7c
	v_add_u32_e32 v48, 16, v46
	s_add_i32 s1, s1, 0
	v_cmp_ge_u32_e32 vcc, v47, v46
	v_cmp_lt_u32_e64 s[6:7], v47, v48
	s_add_i32 s1, s1, 0x11400
	s_and_b64 s[22:23], vcc, s[6:7]
	v_mov_b32_e32 v68, 0xf149f2ca
	v_mov_b32_e32 v69, 0xf149f2ca
	s_waitcnt vmcnt(23)
	v_mfma_f32_16x16x32_bf16 v[32:35], v[32:35], v[4:7], 0
	s_waitcnt vmcnt(22)
	v_mfma_f32_16x16x32_bf16 v[32:35], v[38:41], v[0:3], v[32:35]
	v_sub_u32_e32 v38, v47, v45
	v_max_i32_e32 v38, -15, v38
	s_and_saveexec_b64 s[6:7], s[22:23]
	s_cbranch_execz .LBB0_337
	v_add_u32_e32 v39, 15, v38
	v_min_u32_e32 v39, 30, v39
	v_lshl_add_u32 v39, v39, 2, s1
	ds_read_b32 v69, v39 offset:868
	s_waitcnt lgkmcnt(0)
	v_fmac_f32_e32 v69, 0x3e000000, v32

; __device__ __forceinline__ f32x4 mfma16(bf16x8 a, bf16x8 b, f32x4 c) { return __builtin_amdgcn_mfma_f32_16x16x32_bf16(a, b, c, 0, 0, 0); }
; __device__ __forceinline__ void phase_attn(const Args& a, unsigned char* smem, int tid, int lane, int wave, bf16_t* Yout) {
;     ...
;                 for (int ii = 0; ii < 2; ++ii) {
;                     const int i = bt * 2 + ii;
;                     const float* rp = rpb_s + (rs + i - r + 7) * 31;
; #pragma unroll
;                     for (int hf = 0; hf < 2; ++hf) {
;                         f32x4 s = {0.f, 0.f, 0.f, 0.f};
;                         s = mfma16(kbuf[0][(ii * 2 + hf) * 2], qf0, s); s = mfma16(kbuf[0][(ii * 2 + hf) * 2 + 1], qf1, s);
; #pragma unroll
;                         for (int e = 0; e < 4; ++e) { const int kc = kc0 + 8 * g + 4 * hf + e; const bool ok = (kc >= cs) && (kc < cs + 16);
;                             const int dc = min(max(kc - qc + 15, 0), 30);
;                             s[e] = ok ? s[e] * 0.125f + rp[dc] : -1e30f; }
;                         st[i * 2 + hf] = s;
.LBB0_343:
	s_or_b64 exec, exec, s[6:7]
	s_waitcnt vmcnt(21)
	v_mfma_f32_16x16x32_bf16 v[28:31], v[28:31], v[4:7], 0
	v_or_b32_e32 v32, 4, v47
	v_cmp_ge_u32_e32 vcc, v32, v46
	v_cmp_lt_u32_e64 s[6:7], v32, v48
	s_waitcnt vmcnt(20)
	v_mfma_f32_16x16x32_bf16 v[24:27], v[24:27], v[0:3], v[28:31]
	s_and_b64 s[30:31], vcc, s[6:7]
	v_mov_b32_e32 v72, 0xf149f2ca
	v_mov_b32_e32 v73, 0xf149f2ca
	v_sub_u32_e32 v28, v32, v45
	v_max_i32_e32 v42, -15, v28
	s_and_saveexec_b64 s[6:7], s[30:31]
	s_cbranch_execz .LBB0_345
	v_add_u32_e32 v28, 15, v42
	v_min_u32_e32 v28, 30, v28
	v_lshl_add_u32 v28, v28, 2, s1
	ds_read_b32 v73, v28 offset:868
	s_waitcnt lgkmcnt(0)
	v_fmac_f32_e32 v73, 0x3e000000, v24

; __device__ __forceinline__ f32x4 mfma16(bf16x8 a, bf16x8 b, f32x4 c) { return __builtin_amdgcn_mfma_f32_16x16x32_bf16(a, b, c, 0, 0, 0); }
; __device__ __forceinline__ void phase_attn(const Args& a, unsigned char* smem, int tid, int lane, int wave, bf16_t* Yout) {
;     ...
;                 for (int ii = 0; ii < 2; ++ii) {
;                     const int i = bt * 2 + ii;
;                     const float* rp = rpb_s + (rs + i - r + 7) * 31;
; #pragma unroll
;                     for (int hf = 0; hf < 2; ++hf) {
;                         f32x4 s = {0.f, 0.f, 0.f, 0.f};
;                         s = mfma16(kbuf[0][(ii * 2 + hf) * 2], qf0, s); s = mfma16(kbuf[0][(ii * 2 + hf) * 2 + 1], qf1, s);
; #pragma unroll
;                         for (int e = 0; e < 4; ++e) { const int kc = kc0 + 8 * g + 4 * hf + e; const bool ok = (kc >= cs) && (kc < cs + 16);
;                             const int dc = min(max(kc - qc + 15, 0), 30);
;                             s[e] = ok ? s[e] * 0.125f + rp[dc] : -1e30f; }
;                         st[i * 2 + hf] = s;
.LBB0_351:
	s_or_b64 exec, exec, s[38:39]
	s_waitcnt vmcnt(19)
	v_mfma_f32_16x16x32_bf16 v[20:23], v[20:23], v[4:7], 0
	v_mov_b32_e32 v76, 0xf149f2ca
	v_mov_b32_e32 v77, 0xf149f2ca
	s_waitcnt vmcnt(18)
	v_mfma_f32_16x16x32_bf16 v[16:19], v[16:19], v[0:3], v[20:23]
	s_and_saveexec_b64 s[38:39], s[22:23]
	s_cbranch_execz .LBB0_353
	s_nop 1
	v_add_u32_e32 v20, 15, v38
	v_min_u32_e32 v20, 30, v20
	v_lshl_add_u32 v20, v20, 2, s1
	ds_read_b32 v77, v20 offset:992
	s_waitcnt lgkmcnt(0)
	v_fmac_f32_e32 v77, 0x3e000000, v16

; __device__ __forceinline__ f32x4 mfma16(bf16x8 a, bf16x8 b, f32x4 c) { return __builtin_amdgcn_mfma_f32_16x16x32_bf16(a, b, c, 0, 0, 0); }
; __device__ __forceinline__ void phase_attn(const Args& a, unsigned char* smem, int tid, int lane, int wave, bf16_t* Yout) {
;     ...
;                 for (int ii = 0; ii < 2; ++ii) {
;                     const int i = bt * 2 + ii;
;                     const float* rp = rpb_s + (rs + i - r + 7) * 31;
; #pragma unroll
;                     for (int hf = 0; hf < 2; ++hf) {
;                         f32x4 s = {0.f, 0.f, 0.f, 0.f};
;                         s = mfma16(kbuf[0][(ii * 2 + hf) * 2], qf0, s); s = mfma16(kbuf[0][(ii * 2 + hf) * 2 + 1], qf1, s);
; #pragma unroll
;                         for (int e = 0; e < 4; ++e) { const int kc = kc0 + 8 * g + 4 * hf + e; const bool ok = (kc >= cs) && (kc < cs + 16);
;                             const int dc = min(max(kc - qc + 15, 0), 30);
;                             s[e] = ok ? s[e] * 0.125f + rp[dc] : -1e30f; }
;                         st[i * 2 + hf] = s;
.LBB0_359:
	s_or_b64 exec, exec, s[38:39]
	s_waitcnt vmcnt(17)
	v_mfma_f32_16x16x32_bf16 v[12:15], v[12:15], v[4:7], 0
	v_mov_b32_e32 v80, 0xf149f2ca
	v_mov_b32_e32 v81, 0xf149f2ca
	s_waitcnt vmcnt(16)
	v_mfma_f32_16x16x32_bf16 v[8:11], v[8:11], v[0:3], v[12:15]
	s_and_saveexec_b64 s[38:39], s[30:31]
	s_cbranch_execz .LBB0_361
	s_nop 1
	v_add_u32_e32 v12, 15, v42
	v_min_u32_e32 v12, 30, v12
	v_lshl_add_u32 v12, v12, 2, s1
	ds_read_b32 v81, v12 offset:992
	s_waitcnt lgkmcnt(0)
	v_fmac_f32_e32 v81, 0x3e000000, v8

; __device__ __forceinline__ f32x4 mfma16(bf16x8 a, bf16x8 b, f32x4 c) { return __builtin_amdgcn_mfma_f32_16x16x32_bf16(a, b, c, 0, 0, 0); }
; __device__ __forceinline__ void phase_attn(const Args& a, unsigned char* smem, int tid, int lane, int wave, bf16_t* Yout) {
;     ...
; #pragma unroll
;             for (int bt = 0; bt < 4; ++bt) {
;                 ATT_KLOAD(bt, 0);
;                 asm volatile("" ::: "memory");
; #pragma unroll
;                 for (int ii = 0; ii < 2; ++ii) {
;                     const int i = bt * 2 + ii;
;                     const float* rp = rpb_s + (rs + i - r + 7) * 31;
; #pragma unroll
;                     for (int hf = 0; hf < 2; ++hf) {
;                         f32x4 s = {0.f, 0.f, 0.f, 0.f};
;                         s = mfma16(kbuf[0][(ii * 2 + hf) * 2], qf0, s); s = mfma16(kbuf[0][(ii * 2 + hf) * 2 + 1], qf1, s);
; #pragma unroll
;                         for (int e = 0; e < 4; ++e) { const int kc = kc0 + 8 * g + 4 * hf + e; const bool ok = (kc >= cs) && (kc < cs + 16);
;                             const int dc = min(max(kc - qc + 15, 0), 30);
;                             s[e] = ok ? s[e] * 0.125f + rp[dc] : -1e30f; }
;                         st[i * 2 + hf] = s;
;                     }
.LBB0_367:
	s_or_b64 exec, exec, s[38:39]
	s_add_i32 s38, s12, 0x180
	s_mov_b32 s39, s13
	v_lshl_add_u64 v[12:13], v[36:37], 0, s[38:39]
	s_add_i32 s38, s12, 0x1c0
	v_lshlrev_b64 v[12:13], 11, v[12:13]
	v_lshl_add_u64 v[10:11], v[36:37], 0, s[38:39]
	v_lshl_add_u64 v[12:13], v[130:131], 0, v[12:13]
	v_lshlrev_b64 v[10:11], 11, v[10:11]
	s_mov_b32 s38, 0x2000
	s_mov_b32 s39, 0
	v_lshl_add_u64 v[10:11], v[130:131], 0, v[10:11]
	v_lshl_add_u64 v[14:15], v[12:13], 0, s[38:39]
	v_lshl_add_u64 v[8:9], v[10:11], 0, s[38:39]
	global_load_dwordx4 v[244:247], v[12:13], off
	global_load_dwordx4 v[32:35], v[12:13], off offset:64
	global_load_dwordx4 v[28:31], v[14:15], off
	global_load_dwordx4 v[24:27], v[14:15], off offset:64
	global_load_dwordx4 v[20:23], v[10:11], off
	global_load_dwordx4 v[16:19], v[10:11], off offset:64
	global_load_dwordx4 v[12:15], v[8:9], off
	global_load_dwordx4 v[8:11], v[8:9], off offset:64
	v_mov_b32_e32 v84, 0xf149f2ca
	v_mov_b32_e32 v85, 0xf149f2ca
	s_waitcnt vmcnt(23)
	v_mfma_f32_16x16x32_bf16 v[184:187], v[184:187], v[4:7], 0
	s_waitcnt vmcnt(22)
	v_mfma_f32_16x16x32_bf16 v[188:191], v[188:191], v[0:3], v[184:187]
	s_and_saveexec_b64 s[38:39], s[22:23]
	s_cbranch_execz .LBB0_369
	s_nop 1
	v_add_u32_e32 v184, 15, v38
	v_min_u32_e32 v184, 30, v184
	v_lshl_add_u32 v184, v184, 2, s1
	ds_read_b32 v85, v184 offset:1116
	s_waitcnt lgkmcnt(0)
	v_fmac_f32_e32 v85, 0x3e000000, v188
.LBB0_369:
	s_or_b64 exec, exec, s[38:39]
	s_and_saveexec_b64 s[38:39], s[24:25]
	s_cbranch_execz .LBB0_371
	s_nop 2
	v_add_u32_e32 v188, 15, v39
	v_min_u32_e32 v188, 30, v188
	v_lshl_add_u32 v188, v188, 2, s1
	ds_read_b32 v84, v188 offset:1116
	s_waitcnt lgkmcnt(0)
	v_fmac_f32_e32 v84, 0x3e000000, v189
.LBB0_371:
	s_or_b64 exec, exec, s[38:39]
	v_mov_b32_e32 v86, 0xf149f2ca
	v_mov_b32_e32 v87, 0xf149f2ca
	s_and_saveexec_b64 s[38:39], s[26:27]
	s_cbranch_execz .LBB0_373
	v_add_u32_e32 v188, 15, v40
	v_min_u32_e32 v188, 30, v188
	v_lshl_add_u32 v188, v188, 2, s1
	ds_read_b32 v87, v188 offset:1116
	s_waitcnt lgkmcnt(0)
	v_fmac_f32_e32 v87, 0x3e000000, v190
.LBB0_373:
	s_or_b64 exec, exec, s[38:39]
	s_and_saveexec_b64 s[38:39], s[28:29]
	s_cbranch_execz .LBB0_375
	v_add_u32_e32 v188, 15, v41
	v_min_u32_e32 v188, 30, v188
	v_lshl_add_u32 v188, v188, 2, s1
	ds_read_b32 v86, v188 offset:1116
	s_waitcnt lgkmcnt(0)
	v_fmac_f32_e32 v86, 0x3e000000, v191
.LBB0_375:
	s_or_b64 exec, exec, s[38:39]
	s_waitcnt vmcnt(21)
	v_mfma_f32_16x16x32_bf16 v[192:195], v[192:195], v[4:7], 0
	v_mov_b32_e32 v88, 0xf149f2ca
	v_mov_b32_e32 v89, 0xf149f2ca
	s_waitcnt vmcnt(20)
	v_mfma_f32_16x16x32_bf16 v[196:199], v[196:199], v[0:3], v[192:195]
	s_and_saveexec_b64 s[38:39], s[30:31]
	s_cbranch_execz .LBB0_377
	s_nop 1
	v_add_u32_e32 v192, 15, v42
	v_min_u32_e32 v192, 30, v192
	v_lshl_add_u32 v192, v192, 2, s1
	ds_read_b32 v89, v192 offset:1116
	s_waitcnt lgkmcnt(0)
	v_fmac_f32_e32 v89, 0x3e000000, v196
.LBB0_377:
	s_or_b64 exec, exec, s[38:39]
	s_and_saveexec_b64 s[38:39], s[34:35]
	s_cbranch_execz .LBB0_379
	s_nop 2
	v_add_u32_e32 v196, 15, v43
	v_min_u32_e32 v196, 30, v196
	v_lshl_add_u32 v196, v196, 2, s1
	ds_read_b32 v88, v196 offset:1116
	s_waitcnt lgkmcnt(0)
	v_fmac_f32_e32 v88, 0x3e000000, v197
.LBB0_379:
	s_or_b64 exec, exec, s[38:39]
	v_mov_b32_e32 v90, 0xf149f2ca
	v_mov_b32_e32 v91, 0xf149f2ca
	s_and_saveexec_b64 s[38:39], s[36:37]
	s_cbranch_execz .LBB0_381
	v_add_u32_e32 v196, 15, v44
	v_min_u32_e32 v196, 30, v196
	v_lshl_add_u32 v196, v196, 2, s1
	ds_read_b32 v91, v196 offset:1116
	s_waitcnt lgkmcnt(0)
	v_fmac_f32_e32 v91, 0x3e000000, v198
.LBB0_381:
	s_or_b64 exec, exec, s[38:39]
	s_and_saveexec_b64 s[38:39], s[6:7]
	s_cbranch_execz .LBB0_383
	v_add_u32_e32 v196, 15, v45
	v_min_u32_e32 v196, 30, v196
	v_lshl_add_u32 v196, v196, 2, s1
	ds_read_b32 v90, v196 offset:1116
	s_waitcnt lgkmcnt(0)
	v_fmac_f32_e32 v90, 0x3e000000, v199
.LBB0_383:
	s_or_b64 exec, exec, s[38:39]
	s_waitcnt vmcnt(19)
	v_mfma_f32_16x16x32_bf16 v[200:203], v[200:203], v[4:7], 0
	v_mov_b32_e32 v92, 0xf149f2ca
	v_mov_b32_e32 v93, 0xf149f2ca
	s_waitcnt vmcnt(18)
	v_mfma_f32_16x16x32_bf16 v[204:207], v[204:207], v[0:3], v[200:203]
	s_and_saveexec_b64 s[38:39], s[22:23]
	s_cbranch_execz .LBB0_385
	s_nop 2
	v_add_u32_e32 v200, 15, v38
	v_min_u32_e32 v200, 30, v200
	v_lshl_add_u32 v200, v200, 2, s1
	ds_read_b32 v93, v200 offset:1240
	s_waitcnt lgkmcnt(0)
	v_fmac_f32_e32 v93, 0x3e000000, v204
.LBB0_385:
	s_or_b64 exec, exec, s[38:39]
	s_and_saveexec_b64 s[38:39], s[24:25]
	s_cbranch_execz .LBB0_387
	s_nop 2
	v_add_u32_e32 v204, 15, v39
	v_min_u32_e32 v204, 30, v204
	v_lshl_add_u32 v204, v204, 2, s1
	ds_read_b32 v92, v204 offset:1240
	s_waitcnt lgkmcnt(0)
	v_fmac_f32_e32 v92, 0x3e000000, v205
.LBB0_387:
	s_or_b64 exec, exec, s[38:39]
	v_mov_b32_e32 v94, 0xf149f2ca
	v_mov_b32_e32 v95, 0xf149f2ca
	s_and_saveexec_b64 s[38:39], s[26:27]
	s_cbranch_execz .LBB0_389
	v_add_u32_e32 v204, 15, v40
	v_min_u32_e32 v204, 30, v204
	v_lshl_add_u32 v204, v204, 2, s1
	ds_read_b32 v95, v204 offset:1240
	s_waitcnt lgkmcnt(0)
	v_fmac_f32_e32 v95, 0x3e000000, v206
.LBB0_389:
	s_or_b64 exec, exec, s[38:39]
	s_and_saveexec_b64 s[38:39], s[28:29]
	s_cbranch_execz .LBB0_391
	v_add_u32_e32 v204, 15, v41
	v_min_u32_e32 v204, 30, v204
	v_lshl_add_u32 v204, v204, 2, s1
	ds_read_b32 v94, v204 offset:1240
	s_waitcnt lgkmcnt(0)
	v_fmac_f32_e32 v94, 0x3e000000, v207
.LBB0_391:
	s_or_b64 exec, exec, s[38:39]
	s_waitcnt vmcnt(17)
	v_mfma_f32_16x16x32_bf16 v[208:211], v[208:211], v[4:7], 0
	v_mov_b32_e32 v96, 0xf149f2ca
	v_mov_b32_e32 v97, 0xf149f2ca
	s_waitcnt vmcnt(16)
	v_mfma_f32_16x16x32_bf16 v[212:215], v[212:215], v[0:3], v[208:211]
	s_and_saveexec_b64 s[38:39], s[30:31]
	s_cbranch_execz .LBB0_393
	s_nop 1
	v_add_u32_e32 v208, 15, v42
	v_min_u32_e32 v208, 30, v208
	v_lshl_add_u32 v208, v208, 2, s1
	ds_read_b32 v97, v208 offset:1240
	s_waitcnt lgkmcnt(0)
	v_fmac_f32_e32 v97, 0x3e000000, v212
; __device__ __forceinline__ f32x4 mfma16(bf16x8 a, bf16x8 b, f32x4 c) { return __builtin_amdgcn_mfma_f32_16x16x32_bf16(a, b, c, 0, 0, 0); }
; __device__ __forceinline__ void phase_attn(const Args& a, unsigned char* smem, int tid, int lane, int wave, bf16_t* Yout) {
;     ...
; #pragma unroll
;             for (int bt = 0; bt < 4; ++bt) {
;                 ATT_KLOAD(bt, 0);
;                 asm volatile("" ::: "memory");
; #pragma unroll
;                 for (int ii = 0; ii < 2; ++ii) {
;                     const int i = bt * 2 + ii;
;                     const float* rp = rpb_s + (rs + i - r + 7) * 31;
; #pragma unroll
;                     for (int hf = 0; hf < 2; ++hf) {
;                         f32x4 s = {0.f, 0.f, 0.f, 0.f};
;                         s = mfma16(kbuf[0][(ii * 2 + hf) * 2], qf0, s); s = mfma16(kbuf[0][(ii * 2 + hf) * 2 + 1], qf1, s);
; #pragma unroll
;                         for (int e = 0; e < 4; ++e) { const int kc = kc0 + 8 * g + 4 * hf + e; const bool ok = (kc >= cs) && (kc < cs + 16);
;                             const int dc = min(max(kc - qc + 15, 0), 30);
;                             s[e] = ok ? s[e] * 0.125f + rp[dc] : -1e30f; }
;                         st[i * 2 + hf] = s;
;                     }
.LBB0_393:
	s_or_b64 exec, exec, s[38:39]
	s_and_saveexec_b64 s[38:39], s[34:35]
	s_cbranch_execz .LBB0_395
	s_nop 2
	v_add_u32_e32 v212, 15, v43
	v_min_u32_e32 v212, 30, v212
	v_lshl_add_u32 v212, v212, 2, s1
	ds_read_b32 v96, v212 offset:1240
	s_waitcnt lgkmcnt(0)
	v_fmac_f32_e32 v96, 0x3e000000, v213
.LBB0_395:
	s_or_b64 exec, exec, s[38:39]
	v_mov_b32_e32 v98, 0xf149f2ca
	v_mov_b32_e32 v99, 0xf149f2ca
	s_and_saveexec_b64 s[38:39], s[36:37]
	s_cbranch_execz .LBB0_397
	v_add_u32_e32 v212, 15, v44
	v_min_u32_e32 v212, 30, v212
	v_lshl_add_u32 v212, v212, 2, s1
	ds_read_b32 v99, v212 offset:1240
	s_waitcnt lgkmcnt(0)
	v_fmac_f32_e32 v99, 0x3e000000, v214
.LBB0_397:
	s_or_b64 exec, exec, s[38:39]
	s_and_saveexec_b64 s[38:39], s[6:7]
	s_cbranch_execz .LBB0_399
	v_add_u32_e32 v212, 15, v45
	v_min_u32_e32 v212, 30, v212
	v_lshl_add_u32 v212, v212, 2, s1
	ds_read_b32 v98, v212 offset:1240
	s_waitcnt lgkmcnt(0)
	v_fmac_f32_e32 v98, 0x3e000000, v215
.LBB0_399:
	s_or_b64 exec, exec, s[38:39]
	v_mov_b32_e32 v100, 0xf149f2ca
	v_mov_b32_e32 v101, 0xf149f2ca
	s_waitcnt vmcnt(15)
	v_mfma_f32_16x16x32_bf16 v[52:55], v[52:55], v[4:7], 0
	s_waitcnt vmcnt(14)
	v_mfma_f32_16x16x32_bf16 v[56:59], v[56:59], v[0:3], v[52:55]
	s_and_saveexec_b64 s[38:39], s[22:23]
	s_cbranch_execz .LBB0_401
	s_nop 1
	v_add_u32_e32 v52, 15, v38
	v_min_u32_e32 v52, 30, v52
	v_lshl_add_u32 v52, v52, 2, s1
	ds_read_b32 v101, v52 offset:1364
	s_waitcnt lgkmcnt(0)
	v_fmac_f32_e32 v101, 0x3e000000, v56
.LBB0_401:
	s_or_b64 exec, exec, s[38:39]
	s_and_saveexec_b64 s[38:39], s[24:25]
	s_cbranch_execz .LBB0_403
	s_nop 2
	v_add_u32_e32 v56, 15, v39
	v_min_u32_e32 v56, 30, v56
	v_lshl_add_u32 v56, v56, 2, s1
	ds_read_b32 v100, v56 offset:1364
	s_waitcnt lgkmcnt(0)
	v_fmac_f32_e32 v100, 0x3e000000, v57
.LBB0_403:
	s_or_b64 exec, exec, s[38:39]
	v_mov_b32_e32 v102, 0xf149f2ca
	v_mov_b32_e32 v103, 0xf149f2ca
	s_and_saveexec_b64 s[38:39], s[26:27]
	s_cbranch_execz .LBB0_405
	v_add_u32_e32 v56, 15, v40
	v_min_u32_e32 v56, 30, v56
	v_lshl_add_u32 v56, v56, 2, s1
	ds_read_b32 v103, v56 offset:1364
	s_waitcnt lgkmcnt(0)
	v_fmac_f32_e32 v103, 0x3e000000, v58
.LBB0_405:
	s_or_b64 exec, exec, s[38:39]
	s_and_saveexec_b64 s[38:39], s[28:29]
	s_cbranch_execz .LBB0_407
	v_add_u32_e32 v56, 15, v41
	v_min_u32_e32 v56, 30, v56
	v_lshl_add_u32 v56, v56, 2, s1
	ds_read_b32 v102, v56 offset:1364
	s_waitcnt lgkmcnt(0)
	v_fmac_f32_e32 v102, 0x3e000000, v59
.LBB0_407:
	s_or_b64 exec, exec, s[38:39]
	s_waitcnt vmcnt(13)
	v_mfma_f32_16x16x32_bf16 v[60:63], v[60:63], v[4:7], 0
	v_mov_b32_e32 v104, 0xf149f2ca
	v_mov_b32_e32 v105, 0xf149f2ca
	s_waitcnt vmcnt(12)
	v_mfma_f32_16x16x32_bf16 v[64:67], v[64:67], v[0:3], v[60:63]
	s_and_saveexec_b64 s[38:39], s[30:31]
	s_cbranch_execz .LBB0_409
	s_nop 1
	v_add_u32_e32 v60, 15, v42
	v_min_u32_e32 v60, 30, v60
	v_lshl_add_u32 v60, v60, 2, s1
	ds_read_b32 v105, v60 offset:1364
	s_waitcnt lgkmcnt(0)
	v_fmac_f32_e32 v105, 0x3e000000, v64
.LBB0_409:
	s_or_b64 exec, exec, s[38:39]
	s_and_saveexec_b64 s[38:39], s[34:35]
	s_cbranch_execz .LBB0_411
	s_nop 2
	v_add_u32_e32 v64, 15, v43
	v_min_u32_e32 v64, 30, v64
	v_lshl_add_u32 v64, v64, 2, s1
	ds_read_b32 v104, v64 offset:1364
	s_waitcnt lgkmcnt(0)
	v_fmac_f32_e32 v104, 0x3e000000, v65
.LBB0_411:
	s_or_b64 exec, exec, s[38:39]
	v_mov_b32_e32 v106, 0xf149f2ca
	v_mov_b32_e32 v107, 0xf149f2ca
	s_and_saveexec_b64 s[38:39], s[36:37]
	s_cbranch_execz .LBB0_413
	v_add_u32_e32 v64, 15, v44
	v_min_u32_e32 v64, 30, v64
	v_lshl_add_u32 v64, v64, 2, s1
	ds_read_b32 v107, v64 offset:1364
	s_waitcnt lgkmcnt(0)
	v_fmac_f32_e32 v107, 0x3e000000, v66
; __device__ __forceinline__ f32x4 mfma16(bf16x8 a, bf16x8 b, f32x4 c) { return __builtin_amdgcn_mfma_f32_16x16x32_bf16(a, b, c, 0, 0, 0); }
; __device__ __forceinline__ void phase_attn(const Args& a, unsigned char* smem, int tid, int lane, int wave, bf16_t* Yout) {
;     ...
; #pragma unroll
;             for (int bt = 0; bt < 4; ++bt) {
;                 ATT_KLOAD(bt, 0);
;                 asm volatile("" ::: "memory");
; #pragma unroll
;                 for (int ii = 0; ii < 2; ++ii) {
;                     const int i = bt * 2 + ii;
;                     const float* rp = rpb_s + (rs + i - r + 7) * 31;
; #pragma unroll
;                     for (int hf = 0; hf < 2; ++hf) {
;                         f32x4 s = {0.f, 0.f, 0.f, 0.f};
;                         s = mfma16(kbuf[0][(ii * 2 + hf) * 2], qf0, s); s = mfma16(kbuf[0][(ii * 2 + hf) * 2 + 1], qf1, s);
; #pragma unroll
;                         for (int e = 0; e < 4; ++e) { const int kc = kc0 + 8 * g + 4 * hf + e; const bool ok = (kc >= cs) && (kc < cs + 16);
;                             const int dc = min(max(kc - qc + 15, 0), 30);
;                             s[e] = ok ? s[e] * 0.125f + rp[dc] : -1e30f; }
;                         st[i * 2 + hf] = s;
;                     }
.LBB0_413:
	s_or_b64 exec, exec, s[38:39]
	s_and_saveexec_b64 s[38:39], s[6:7]
	s_cbranch_execz .LBB0_415
	v_add_u32_e32 v64, 15, v45
	v_min_u32_e32 v64, 30, v64
	v_lshl_add_u32 v64, v64, 2, s1
	ds_read_b32 v106, v64 offset:1364
	s_waitcnt lgkmcnt(0)
	v_fmac_f32_e32 v106, 0x3e000000, v67
.LBB0_415:
	s_or_b64 exec, exec, s[38:39]
	s_waitcnt vmcnt(11)
	v_mfma_f32_16x16x32_bf16 v[228:231], v[228:231], v[4:7], 0
	v_mov_b32_e32 v108, 0xf149f2ca
	v_mov_b32_e32 v109, 0xf149f2ca
	s_waitcnt vmcnt(10)
	v_mfma_f32_16x16x32_bf16 v[232:235], v[232:235], v[0:3], v[228:231]
	s_and_saveexec_b64 s[38:39], s[22:23]
	s_cbranch_execz .LBB0_417
	s_nop 2
	v_add_u32_e32 v228, 15, v38
	v_min_u32_e32 v228, 30, v228
	v_lshl_add_u32 v228, v228, 2, s1
	ds_read_b32 v109, v228 offset:1488
	s_waitcnt lgkmcnt(0)
	v_fmac_f32_e32 v109, 0x3e000000, v232
.LBB0_417:
	s_or_b64 exec, exec, s[38:39]
	s_and_saveexec_b64 s[38:39], s[24:25]
	s_cbranch_execz .LBB0_419
	s_nop 2
	v_add_u32_e32 v232, 15, v39
	v_min_u32_e32 v232, 30, v232
	v_lshl_add_u32 v232, v232, 2, s1
	ds_read_b32 v108, v232 offset:1488
	s_waitcnt lgkmcnt(0)
	v_fmac_f32_e32 v108, 0x3e000000, v233
.LBB0_419:
	s_or_b64 exec, exec, s[38:39]
	v_mov_b32_e32 v110, 0xf149f2ca
	v_mov_b32_e32 v111, 0xf149f2ca
	s_and_saveexec_b64 s[38:39], s[26:27]
	s_cbranch_execz .LBB0_421
	v_add_u32_e32 v232, 15, v40
	v_min_u32_e32 v232, 30, v232
	v_lshl_add_u32 v232, v232, 2, s1
	ds_read_b32 v111, v232 offset:1488
	s_waitcnt lgkmcnt(0)
	v_fmac_f32_e32 v111, 0x3e000000, v234
.LBB0_421:
	s_or_b64 exec, exec, s[38:39]
	s_and_saveexec_b64 s[38:39], s[28:29]
	s_cbranch_execz .LBB0_423
	v_add_u32_e32 v232, 15, v41
	v_min_u32_e32 v232, 30, v232
	v_lshl_add_u32 v232, v232, 2, s1
	ds_read_b32 v110, v232 offset:1488
	s_waitcnt lgkmcnt(0)
	v_fmac_f32_e32 v110, 0x3e000000, v235
.LBB0_423:
	s_or_b64 exec, exec, s[38:39]
	s_waitcnt vmcnt(9)
	v_mfma_f32_16x16x32_bf16 v[236:239], v[236:239], v[4:7], 0
	v_mov_b32_e32 v147, 0xf149f2ca
	v_mov_b32_e32 v148, 0xf149f2ca
	s_waitcnt vmcnt(8)
	v_mfma_f32_16x16x32_bf16 v[240:243], v[240:243], v[0:3], v[236:239]
	s_and_saveexec_b64 s[38:39], s[30:31]
	s_cbranch_execz .LBB0_425
	s_nop 1
	v_add_u32_e32 v236, 15, v42
	v_min_u32_e32 v236, 30, v236
	v_lshl_add_u32 v236, v236, 2, s1
	ds_read_b32 v148, v236 offset:1488
	s_waitcnt lgkmcnt(0)
	v_fmac_f32_e32 v148, 0x3e000000, v240
.LBB0_425:
	s_or_b64 exec, exec, s[38:39]
	s_and_saveexec_b64 s[38:39], s[34:35]
	s_cbranch_execz .LBB0_427
	s_nop 2
	v_add_u32_e32 v240, 15, v43
	v_min_u32_e32 v240, 30, v240
	v_lshl_add_u32 v240, v240, 2, s1
	ds_read_b32 v147, v240 offset:1488
	s_waitcnt lgkmcnt(0)
	v_fmac_f32_e32 v147, 0x3e000000, v241
.LBB0_427:
	s_or_b64 exec, exec, s[38:39]
	v_mov_b32_e32 v149, 0xf149f2ca
	v_mov_b32_e32 v150, 0xf149f2ca
	s_and_saveexec_b64 s[38:39], s[36:37]
	s_cbranch_execz .LBB0_429
	v_add_u32_e32 v240, 15, v44
	v_min_u32_e32 v240, 30, v240
	v_lshl_add_u32 v240, v240, 2, s1
	ds_read_b32 v150, v240 offset:1488
	s_waitcnt lgkmcnt(0)
	v_fmac_f32_e32 v150, 0x3e000000, v242
.LBB0_429:
	s_or_b64 exec, exec, s[38:39]
	s_and_saveexec_b64 s[38:39], s[6:7]
	s_cbranch_execz .LBB0_431
	v_add_u32_e32 v240, 15, v45
	v_min_u32_e32 v240, 30, v240
	v_lshl_add_u32 v240, v240, 2, s1
	ds_read_b32 v149, v240 offset:1488
	s_waitcnt lgkmcnt(0)
	v_fmac_f32_e32 v149, 0x3e000000, v243
.LBB0_431:
	s_or_b64 exec, exec, s[38:39]
	v_mov_b32_e32 v151, 0xf149f2ca
	v_mov_b32_e32 v152, 0xf149f2ca
	s_waitcnt vmcnt(7)
	v_mfma_f32_16x16x32_bf16 v[244:247], v[244:247], v[4:7], 0
	s_waitcnt vmcnt(6)
	v_mfma_f32_16x16x32_bf16 v[32:35], v[32:35], v[0:3], v[244:247]
	s_and_saveexec_b64 s[38:39], s[22:23]
	s_cbranch_execz .LBB0_433
	v_add_u32_e32 v36, 15, v38
	v_min_u32_e32 v36, 30, v36
	v_lshl_add_u32 v36, v36, 2, s1
	ds_read_b32 v152, v36 offset:1612
	s_waitcnt lgkmcnt(0)
	s_nop 0
	v_fmac_f32_e32 v152, 0x3e000000, v32

; __device__ __forceinline__ f32x4 mfma16(bf16x8 a, bf16x8 b, f32x4 c) { return __builtin_amdgcn_mfma_f32_16x16x32_bf16(a, b, c, 0, 0, 0); }
; __device__ __forceinline__ void phase_attn(const Args& a, unsigned char* smem, int tid, int lane, int wave, bf16_t* Yout) {
;     ...
;                         f32x4 s = {0.f, 0.f, 0.f, 0.f};
;                         s = mfma16(kbuf[0][(ii * 2 + hf) * 2], qf0, s); s = mfma16(kbuf[0][(ii * 2 + hf) * 2 + 1], qf1, s);
; #pragma unroll
;                         for (int e = 0; e < 4; ++e) { const int kc = kc0 + 8 * g + 4 * hf + e; const bool ok = (kc >= cs) && (kc < cs + 16);
;                             const int dc = min(max(kc - qc + 15, 0), 30);
;                             s[e] = ok ? s[e] * 0.125f + rp[dc] : -1e30f; }
.LBB0_439:
	s_or_b64 exec, exec, s[38:39]
	s_waitcnt vmcnt(5)
	v_mfma_f32_16x16x32_bf16 v[28:31], v[28:31], v[4:7], 0
	v_mov_b32_e32 v155, 0xf149f2ca
	v_mov_b32_e32 v216, 0xf149f2ca
	s_waitcnt vmcnt(4)
	v_mfma_f32_16x16x32_bf16 v[24:27], v[24:27], v[0:3], v[28:31]
	s_and_saveexec_b64 s[38:39], s[30:31]
	s_cbranch_execz .LBB0_441
	s_nop 1
	v_add_u32_e32 v28, 15, v42
	v_min_u32_e32 v28, 30, v28
	v_lshl_add_u32 v28, v28, 2, s1
	ds_read_b32 v216, v28 offset:1612
	s_waitcnt lgkmcnt(0)
	v_fmac_f32_e32 v216, 0x3e000000, v24

; __device__ __forceinline__ f32x4 mfma16(bf16x8 a, bf16x8 b, f32x4 c) { return __builtin_amdgcn_mfma_f32_16x16x32_bf16(a, b, c, 0, 0, 0); }
; __device__ __forceinline__ void phase_attn(const Args& a, unsigned char* smem, int tid, int lane, int wave, bf16_t* Yout) {
;     ...
;                         f32x4 s = {0.f, 0.f, 0.f, 0.f};
;                         s = mfma16(kbuf[0][(ii * 2 + hf) * 2], qf0, s); s = mfma16(kbuf[0][(ii * 2 + hf) * 2 + 1], qf1, s);
; #pragma unroll
;                         for (int e = 0; e < 4; ++e) { const int kc = kc0 + 8 * g + 4 * hf + e; const bool ok = (kc >= cs) && (kc < cs + 16);
;                             const int dc = min(max(kc - qc + 15, 0), 30);
;                             s[e] = ok ? s[e] * 0.125f + rp[dc] : -1e30f; }
.LBB0_447:
	s_or_b64 exec, exec, s[38:39]
	s_waitcnt vmcnt(3)
	v_mfma_f32_16x16x32_bf16 v[20:23], v[20:23], v[4:7], 0
	v_mov_b32_e32 v219, 0xf149f2ca
	v_mov_b32_e32 v220, 0xf149f2ca
	s_waitcnt vmcnt(2)
	v_mfma_f32_16x16x32_bf16 v[16:19], v[16:19], v[0:3], v[20:23]
	s_and_saveexec_b64 s[38:39], s[22:23]
	s_cbranch_execz .LBB0_449
	s_nop 2
	v_add_u32_e32 v20, 15, v38
	v_min_u32_e32 v20, 30, v20
	v_lshl_add_u32 v20, v20, 2, s1
	ds_read_b32 v220, v20 offset:1736
	s_waitcnt lgkmcnt(0)
	v_fmac_f32_e32 v220, 0x3e000000, v16
